# attention units: static priority 1 for waves 4-7 (second wave of each SIMD), restored to 0 afterwards
# speedup vs baseline: 1.0033x; 1.0033x over previous
.LBB0_444:
	s_andn2_b64 vcc, exec, s[4:5]
	s_cbranch_vccnz .LBB0_549
	v_readlane_b32 s6, v253, 2
	s_mov_b64 s[4:5], s[96:97]
	v_readlane_b32 s7, v253, 3
	s_load_dword s70, s[6:7], 0x0
	v_readlane_b32 s6, v254, 32
	v_readlane_b32 s7, v254, 33
	s_andn2_b64 vcc, exec, s[6:7]
	s_cbranch_vccnz .LBB0_471
	v_readfirstlane_b32 s100, v0
	s_nop 3
	s_cmp_lt_u32 s100, 0x100
	s_cbranch_scc1 .Lattn_prio_done
	s_setprio 1
.Lattn_prio_done:
	s_load_dwordx2 s[4:5], s[4:5], 0xb8
	s_mov_b32 s77, s2
	s_waitcnt lgkmcnt(0)
	s_add_u32 s68, s4, 0x35024000
	s_addc_u32 s69, s5, 0
	s_add_u32 s71, s4, 0x33f24000
	s_addc_u32 s72, s5, 0
	s_add_u32 s73, s4, 0x347a4000
	s_addc_u32 s74, s5, 0
	s_add_u32 s75, s4, 0x2c824000
	s_addc_u32 s76, s5, 0
	s_cmpk_lg_i32 s70, 0x100
	s_cselect_b64 s[44:45], -1, 0
	s_add_u32 s46, s4, 0x347c8000
	s_addc_u32 s47, s5, 0
	s_branch .LBB0_448

.LBB0_471:
	s_setprio 0
	v_mov_b64_e32 v[200:201], 0x100
	v_mov_b64_e32 v[202:203], 0xff
	v_mov_b64_e32 v[204:205], 0x80
	v_mov_b64_e32 v[206:207], 0x7f
	v_readlane_b32 s6, v253, 4
	s_mov_b64 s[4:5], s[96:97]
	v_mov_b32_e32 v10, v0
	v_readlane_b32 s7, v253, 5
	s_andn2_b64 vcc, exec, s[6:7]
	v_readfirstlane_b32 s10, v10
	s_cbranch_vccnz .LBB0_491
	v_lshlrev_b32_e32 v2, 4, v10
	v_add_u32_e32 v3, 0x2000, v2
	v_ashrrev_i32_e32 v4, 31, v3
	v_lshrrev_b32_e32 v4, 22, v4
	v_add_u32_e32 v4, v3, v4
	v_ashrrev_i32_e32 v4, 10, v4
	v_mul_i32_i24_e32 v5, 0x400, v4
	v_sub_u32_e32 v3, v3, v5
	v_lshrrev_b32_e32 v5, 4, v3
	v_bitop3_b32 v3, v5, v3, 32 bitop3:0x6c
	v_ashrrev_i32_e32 v5, 31, v3
	v_lshrrev_b32_e32 v5, 26, v5
	v_add_u32_e32 v5, v3, v5
	v_lshlrev_b32_e32 v7, 3, v4
	v_ashrrev_i32_e32 v6, 6, v5
	v_and_b32_e32 v7, -16, v7
	v_and_b32_e32 v5, 0xc0, v5
	v_add_u32_e32 v7, v6, v7
	v_sub_u32_e32 v3, v3, v5
	s_load_dwordx2 s[20:21], s[4:5], 0xb8
	v_and_b32_e32 v6, 3, v6
	s_mov_b32 s4, 0x7fffe0
	v_lshrrev_b32_e32 v8, 2, v7
	v_lshlrev_b32_e32 v9, 1, v7
	v_lshlrev_b32_e32 v4, 5, v4
	v_ashrrev_i16_sdwa v3, v226, sext(v3) dst_sel:DWORD dst_unused:UNUSED_PAD src0_sel:DWORD src1_sel:BYTE_0
	v_and_or_b32 v6, v7, s4, v6
	v_and_b32_e32 v8, 4, v8
	v_and_b32_e32 v9, 24, v9
	v_and_b32_e32 v4, 32, v4
	v_bfe_i32 v3, v3, 0, 16
	v_or3_b32 v6, v6, v8, v9
	v_add_lshl_u32 v3, v4, v3, 1
	v_lshl_add_u32 v132, v6, 9, v3
	v_lshl_add_u32 v134, v7, 9, v3
	v_bfe_i32 v3, v10, 27, 1
	v_lshrrev_b32_e32 v3, 22, v3
	v_add_u32_e32 v3, v2, v3
	v_and_b32_e32 v3, 0xfffffc00, v3
	v_sub_u32_e32 v2, v2, v3
	v_lshrrev_b32_e32 v3, 4, v2
	v_ashrrev_i32_e32 v5, 31, v10
	v_bitop3_b32 v2, v3, v2, 32 bitop3:0x6c
	v_lshrrev_b32_e32 v5, 26, v5
	v_ashrrev_i32_e32 v3, 31, v2
	v_add_u32_e32 v5, v10, v5
	s_waitcnt lgkmcnt(0)
	s_add_u32 s6, s20, 0x18100000
	v_lshrrev_b32_e32 v3, 26, v3
	v_ashrrev_i32_e32 v5, 6, v5
	s_addc_u32 s7, s21, 0
	v_add_u32_e32 v3, v2, v3
	v_lshlrev_b32_e32 v6, 3, v5
	s_add_u32 s8, s20, 0x31d24000
	v_ashrrev_i32_e32 v4, 6, v3
	v_and_b32_e32 v6, -16, v6
	v_and_b32_e32 v3, 0xc0, v3
	s_addc_u32 s9, s21, 0
	s_ashr_i32 s36, s10, 6
	v_add_u32_e32 v6, v4, v6
	v_and_b32_e32 v4, 3, v4
	v_sub_u32_e32 v2, v2, v3
	s_ashr_i32 s11, s10, 8
	s_lshl_b32 s52, s36, 10
	v_and_or_b32 v4, v6, s4, v4
	v_lshrrev_b32_e32 v7, 2, v6
	v_lshlrev_b32_e32 v8, 1, v6
	v_lshlrev_b32_e32 v5, 5, v5
	v_ashrrev_i16_sdwa v2, v226, sext(v2) dst_sel:DWORD dst_unused:UNUSED_PAD src0_sel:DWORD src1_sel:BYTE_0
	v_readlane_b32 s4, v254, 56
	v_and_b32_e32 v7, 4, v7
	v_and_b32_e32 v8, 24, v8
	v_and_b32_e32 v5, 32, v5
	v_bfe_i32 v2, v2, 0, 16
	v_readlane_b32 s5, v254, 57
	s_add_u32 s54, s8, s4
	v_or3_b32 v4, v4, v7, v8
	v_add_lshl_u32 v2, v5, v2, 1
	s_addc_u32 s55, s9, s5
	s_add_i32 s71, s52, 0
	v_lshl_add_u32 v136, v4, 9, v2
	s_add_i32 m0, s71, 0x10000
	v_lshl_add_u32 v138, v6, 9, v2
	global_load_lds_dwordx4 v136, s[54:55]
	s_add_i32 m0, s71, 0x12000
	s_add_u32 s4, s54, 0x10000
	global_load_lds_dwordx4 v132, s[54:55]
	s_addc_u32 s5, s55, 0
	s_add_i32 m0, s71, 0x14000
	v_mov_b32_e32 v137, v99
	global_load_lds_dwordx4 v136, s[4:5]
	s_add_i32 m0, s71, 0x16000
	v_mov_b32_e32 v133, v99
	global_load_lds_dwordx4 v132, s[4:5]
	v_readlane_b32 s4, v254, 54
	v_readlane_b32 s5, v254, 55
	s_add_u32 s56, s6, s4
	s_addc_u32 s57, s7, s5
	s_add_i32 s72, s71, 0x2000
	s_mov_b32 m0, s71
	s_add_u32 s4, s56, 0x10000
	global_load_lds_dwordx4 v138, s[56:57]
	s_mov_b32 m0, s72
	s_addc_u32 s5, s57, 0
	s_add_i32 s73, s71, 0x4000
	global_load_lds_dwordx4 v134, s[56:57]
	s_mov_b32 m0, s73
	s_add_i32 s74, s71, 0x6000
	global_load_lds_dwordx4 v138, s[4:5]
	s_mov_b32 m0, s74
	v_mov_b32_e32 v139, v99
	global_load_lds_dwordx4 v134, s[4:5]
	v_mov_b32_e32 v135, v99
	s_cmp_eq_u32 s11, 1
	v_lshl_add_u64 v[8:9], s[54:55], 0, v[136:137]
	v_lshl_add_u64 v[6:7], s[54:55], 0, v[132:133]
	v_lshl_add_u64 v[2:3], s[56:57], 0, v[138:139]
	s_cselect_b64 s[4:5], -1, 0
	s_cmp_lg_u32 s11, 1
	v_lshl_add_u64 v[4:5], s[56:57], 0, v[134:135]
	s_cbranch_scc1 .LBB0_474
	s_barrier
